# counted lgkmcnt waits in STEP0 PV0 (lgkmcnt(0) right after issuing V fragment reloads replaced by per-consumer waits 6/2/0)
# baseline (speedup 1.0000x reference)
; __device__ __forceinline__ void sm_half(f32x16& p, float& m_reg, float& l_reg, float& alpha, bf16x8& paL, bf16x8& paH) {
;   float a = fmaxf(fmaxf(p[0], p[1]), p[2]), b = fmaxf(fmaxf(p[3], p[4]), p[5]);
;   a = fmaxf(fmaxf(a, p[6]), p[7]); b = fmaxf(fmaxf(b, p[8]), p[9]); a = fmaxf(fmaxf(a, p[10]), p[11]); b = fmaxf(fmaxf(b, p[12]), p[13]); a = fmaxf(fmaxf(a, p[14]), p[15]);
;   float pmax = fmaxf(a, b);
;   { auto rr = __builtin_amdgcn_permlane32_swap(__float_as_uint(pmax), __float_as_uint(pmax), false, false);
;     pmax = fmaxf(__uint_as_float(rr[0]), __uint_as_float(rr[1])); }
;   const bool keep = __all(pmax - m_reg <= THRL);
;   const float mn = keep ? m_reg : fmaxf(m_reg, pmax);
;   alpha = __builtin_amdgcn_exp2f(m_reg - mn); m_reg = mn;
; #pragma unroll
;   for (int r = 0; r < 16; ++r) p[r] = __builtin_amdgcn_exp2f(p[r] - mn);
;   float ps = 0;
; #pragma unroll
;   for (int r = 0; r < 16; ++r) ps += p[r];
;   { auto rr = __builtin_amdgcn_permlane32_swap(__float_as_uint(ps), __float_as_uint(ps), false, false);
;     ps = __uint_as_float(rr[0]) + __uint_as_float(rr[1]); }
;   l_reg = l_reg * alpha + ps;
;     ...
;   PK4(p, 0, paL); PK4(p, 8, paH);
;     ...
; }
; template <int H> __device__ __forceinline__ void qkt_half(f32x16& p, const char* Kn, const char* Kr, const bf16x8* qr, int r32, int hi) {
;   p = f32x16{};
; #pragma unroll
;   for (int d0 = 0; d0 < 8; ++d0) { const int cb = (d0 * 16 + hi * 8) * 2;
;     const bf16x8 f = *reinterpret_cast<const bf16x8*>(Kn + KSWZ(32 * H + r32, cb)); p = __builtin_amdgcn_mfma_f32_32x32x16_bf16(f, qr[d0], p, 0, 0, 0); }
; #pragma unroll
;   for (int d0 = 0; d0 < 4; ++d0) { const int cb = (d0 * 16 + hi * 8) * 2;
;     const bf16x8 f = *reinterpret_cast<const bf16x8*>(Kr + KRSWZ(32 * H + r32, cb)); p = __builtin_amdgcn_mfma_f32_32x32x16_bf16(f, qr[8 + d0], p, 0, 0, 0); }
; }
; template <int H, int D0> __device__ __forceinline__ VFrag pv_rd(int vb) {
;   VFrag f; f.l0 = tr_read<v_rd_off(D0, 2 * H, 0)>(vb); f.h0 = tr_read<v_rd_off(D0, 2 * H, 1)>(vb); f.l1 = tr_read<v_rd_off(D0, 2 * H + 1, 0)>(vb); f.h1 = tr_read<v_rd_off(D0, 2 * H + 1, 1)>(vb); return f;
; }
; __device__ __forceinline__ void pv_mma(f32x16& od, VFrag& f, bf16x8 paL, bf16x8 paH) {
;     ...
;   od = __builtin_amdgcn_mfma_f32_32x32x16_bf16(paL, PK(f.l0, f.h0), od, 0, 0, 0);
;   od = __builtin_amdgcn_mfma_f32_32x32x16_bf16(paH, PK(f.l1, f.h1), od, 0, 0, 0);
;     ...
; }
.LBB0_525:
.LBB0_527:
	s_waitcnt lgkmcnt(4)
	v_mfma_f32_32x32x16_bf16 v[50:65], v[82:85], v[90:93], v[50:65]
	ds_read_b64_tr_b16 v[90:91], v175 offset:0x400
	ds_read_b64_tr_b16 v[92:93], v175 offset:0xc00
	ds_read_b64_tr_b16 v[210:211], v175 offset:0x1400
	ds_read_b64_tr_b16 v[212:213], v175 offset:0x1c00
	s_waitcnt lgkmcnt(4)
	ds_read_b64_tr_b16 v[214:215], v175 offset:0x600
	ds_read_b64_tr_b16 v[216:217], v175 offset:0xe00
	v_mfma_f32_32x32x16_bf16 v[50:65], v[86:89], v[94:97], v[50:65]
	ds_read_b64_tr_b16 v[94:95], v175 offset:0x1600
	ds_read_b64_tr_b16 v[96:97], v175 offset:0x1e00
	s_nop 0
	s_nop 0
	v_mfma_f32_32x32x16_bf16 v[34:49], v[82:85], v[202:205], v[34:49]
	v_max_f32_e32 v201, v66, v67
	v_max3_f32 v202, v69, v70, v71
	v_max3_f32 v201, v201, v68, v72
	v_max3_f32 v202, v202, v74, v75
	v_max3_f32 v201, v201, v73, v76
	v_max3_f32 v202, v202, v78, v79
	v_max3_f32 v201, v201, v77, v80
	v_max3_f32 v201, v201, v81, v202
	v_mov_b32_e32 v202, v201
	s_nop 1
	v_permlane32_swap_b32_e32 v201, v202
	s_waitcnt lgkmcnt(6)
	v_mfma_f32_32x32x16_bf16 v[18:33], v[82:85], v[90:93], v[18:33]
	v_max_f32_e32 v90, v201, v202
	v_cmp_ge_f32_e32 vcc, s99, v90
	s_cmp_eq_u64 vcc, exec
	s_cbranch_scc0 .Lrare_01
	v_mov_b32_e32 v200, 1.0
.Lcont_01:
	v_exp_f32_e32 v66, v66
	v_exp_f32_e32 v67, v67
	v_exp_f32_e32 v68, v68
	v_exp_f32_e32 v69, v69
	s_waitcnt lgkmcnt(2)
	v_mfma_f32_32x32x16_bf16 v[2:17], v[82:85], v[214:217], v[2:17]
	v_exp_f32_e32 v70, v70
	v_exp_f32_e32 v71, v71
	v_add_f32_e32 v201, v67, v66
	v_exp_f32_e32 v72, v72
	v_add_f32_e32 v201, v68, v201
	v_exp_f32_e32 v73, v73
	v_add_f32_e32 v201, v69, v201
	v_add_f32_e32 v201, v70, v201
	v_add_f32_e32 v201, v71, v201
	v_add_f32_e32 v201, v72, v201
	v_add_f32_e32 v201, v73, v201
	v_mfma_f32_32x32x16_bf16 v[34:49], v[86:89], v[206:209], v[34:49]
	v_mfma_f32_32x32x16_bf16 v[18:33], v[86:89], v[210:213], v[18:33]
	v_cvt_pk_bf16_f32 v66, v66, v67
	v_cvt_pk_bf16_f32 v67, v68, v69
	s_waitcnt lgkmcnt(0)
	v_mfma_f32_32x32x16_bf16 v[2:17], v[86:89], v[94:97], v[2:17]
	v_cvt_pk_bf16_f32 v68, v70, v71
	v_cvt_pk_bf16_f32 v69, v72, v73
	s_nop 0
	v_permlane32_swap_b32_e32 v66, v68
	v_permlane32_swap_b32_e32 v67, v69
	s_cbranch_scc1 .LBB0_531
	s_and_saveexec_b64 s[62:63], s[0:1]
	ds_write_b32 v196, v200 offset:128
	s_or_b64 exec, exec, s[62:63]
	s_waitcnt lgkmcnt(0)
	v_add_u32_e32 v86, s80, v176
	ds_read_b128 v[90:93], v86 offset:224
	ds_read_b128 v[94:97], v86 offset:192
	ds_read_b128 v[82:85], v86 offset:160
	ds_read_b128 v[86:89], v86 offset:128
	s_waitcnt lgkmcnt(0)
	v_pk_mul_f32 v[62:63], v[62:63], v[90:91]
	v_pk_mul_f32 v[58:59], v[58:59], v[94:95]
	v_pk_mul_f32 v[54:55], v[54:55], v[82:83]
	v_pk_mul_f32 v[64:65], v[64:65], v[92:93]
	v_pk_mul_f32 v[60:61], v[60:61], v[96:97]
	v_pk_mul_f32 v[56:57], v[56:57], v[84:85]
	v_pk_mul_f32 v[52:53], v[52:53], v[88:89]
	v_pk_mul_f32 v[50:51], v[50:51], v[86:87]
	v_pk_mul_f32 v[46:47], v[46:47], v[90:91]
	v_pk_mul_f32 v[42:43], v[42:43], v[94:95]
	v_pk_mul_f32 v[38:39], v[38:39], v[82:83]
	v_pk_mul_f32 v[48:49], v[48:49], v[92:93]
	v_pk_mul_f32 v[44:45], v[44:45], v[96:97]
	v_pk_mul_f32 v[40:41], v[40:41], v[84:85]
	v_pk_mul_f32 v[36:37], v[36:37], v[88:89]
	v_pk_mul_f32 v[34:35], v[34:35], v[86:87]
	v_pk_mul_f32 v[30:31], v[30:31], v[90:91]
	v_pk_mul_f32 v[26:27], v[26:27], v[94:95]
	v_pk_mul_f32 v[22:23], v[22:23], v[82:83]
	v_pk_mul_f32 v[32:33], v[32:33], v[92:93]
	v_pk_mul_f32 v[28:29], v[28:29], v[96:97]
	v_pk_mul_f32 v[24:25], v[24:25], v[84:85]
	v_pk_mul_f32 v[20:21], v[20:21], v[88:89]
	v_pk_mul_f32 v[18:19], v[18:19], v[86:87]
	v_pk_mul_f32 v[14:15], v[14:15], v[90:91]
	v_pk_mul_f32 v[10:11], v[10:11], v[94:95]
	v_pk_mul_f32 v[6:7], v[6:7], v[82:83]
	v_pk_mul_f32 v[16:17], v[16:17], v[92:93]
	v_pk_mul_f32 v[12:13], v[12:13], v[96:97]
	v_pk_mul_f32 v[8:9], v[8:9], v[84:85]
	v_pk_mul_f32 v[4:5], v[4:5], v[88:89]
	v_pk_mul_f32 v[2:3], v[2:3], v[86:87]
